# attention main loop PV half: the 8 PV MFMAs reordered into two 4-long accumulator chains (K-fragment reads that reuse a V register moved behind its consumer)
# baseline (speedup 1.0000x reference)
; #define WAIT_BAR(N) asm volatile("s_waitcnt vmcnt(" #N ") lgkmcnt(0)\n\ts_barrier" ::: "memory")
; #define RESC() do { if (resc) { asm volatile("s_waitcnt lgkmcnt(0)" ::: "memory"); \
;       _Pragma("unroll") for (int d_ = 0; d_ < 2; ++d_) _Pragma("unroll") for (int r = 0; r < 16; ++r) o[d_][r] *= wsf[crow(r, hi)]; } } while (0)
; #define ROT() do { sl_prev = sl_cur; sl_cur = sl_next; sl_next = (sl_next == (NSLOT - 1) * SLOTB) ? 0 : sl_next + SLOTB; } while (0)
; template <int THRL> __device__ __forceinline__ void attn_unit(int b, int h, int qb, const f16_t* Q, const f16_t* __restrict__ K, const f16_t* __restrict__ V, f16_t* O, const float* __restrict__ kms, char* shm) {
;     ...
;     int t = 1;
;     for (; t + 5 < NT; t += 2) {
;         STEP(pB0, pB1, pA0, pA1, t, true, true, true);     WAIT_BAR(2); RESC(); ROT();
.LBB0_543:
	s_waitcnt lgkmcnt(0)
	v_mfma_f32_32x32x16_f16 v[18:33], v[142:145], v[178:181], v[18:33]
	v_exp_f32_e32 v98, v98
	v_exp_f32_e32 v99, v99
	v_exp_f32_e32 v100, v100
	v_exp_f32_e32 v101, v101
	v_mfma_f32_32x32x16_f16 v[18:33], v[134:137], v[66:69], v[18:33]
	v_exp_f32_e32 v102, v102
	v_exp_f32_e32 v103, v103
	v_exp_f32_e32 v104, v104
	v_exp_f32_e32 v105, v105
	v_add_u32_e32 v78, s30, v211
	ds_read_b128 v[62:65], v78
	v_mfma_f32_32x32x16_f16 v[18:33], v[126:129], v[74:77], v[18:33]
	v_exp_f32_e32 v106, v106
	v_exp_f32_e32 v107, v107
	v_exp_f32_e32 v108, v108
	v_exp_f32_e32 v109, v109
	ds_read_b128 v[178:181], v78 offset:2048
	ds_read_b128 v[170:173], v78 offset:2560
	v_mfma_f32_32x32x16_f16 v[18:33], v[122:125], v[54:57], v[18:33]
	v_exp_f32_e32 v110, v110
	v_exp_f32_e32 v111, v111
	v_exp_f32_e32 v112, v112
	v_exp_f32_e32 v113, v113
	ds_read_b128 v[166:169], v78 offset:4096
	ds_read_b128 v[162:165], v78 offset:4608
	v_mfma_f32_32x32x16_f16 v[2:17], v[142:145], v[174:177], v[2:17]
	v_exp_f32_e32 v82, v82
	v_exp_f32_e32 v83, v83
	v_exp_f32_e32 v84, v84
	v_exp_f32_e32 v85, v85
	ds_read_b128 v[158:161], v78 offset:6144
	ds_read_b128 v[146:149], v78 offset:6656
	ds_read_b128 v[174:177], v78 offset:512
	v_mfma_f32_32x32x16_f16 v[2:17], v[134:137], v[70:73], v[2:17]
	v_exp_f32_e32 v86, v86
	v_exp_f32_e32 v87, v87
	v_exp_f32_e32 v88, v88
	v_exp_f32_e32 v89, v89
	v_mfma_f32_32x32x16_f16 v[2:17], v[126:129], v[50:53], v[2:17]
	v_exp_f32_e32 v90, v90
	v_exp_f32_e32 v91, v91
	v_exp_f32_e32 v92, v92
	v_exp_f32_e32 v93, v93
	v_mfma_f32_32x32x16_f16 v[2:17], v[122:125], v[58:61], v[2:17]
	v_exp_f32_e32 v94, v94
	v_exp_f32_e32 v95, v95
	v_exp_f32_e32 v96, v96
	v_exp_f32_e32 v97, v97
	s_waitcnt vmcnt(2) lgkmcnt(0)
	s_barrier
	s_andn2_b64 vcc, exec, s[8:9]
	v_add_u32_e32 v192, s88, v213
	s_cbranch_vccnz .LBB0_545
	s_waitcnt lgkmcnt(0)
	ds_read_b128 v[50:53], v192 offset:49248
	ds_read_b128 v[54:57], v192 offset:49216
	ds_read_b128 v[58:61], v192 offset:49184
	ds_read_b128 v[66:69], v192 offset:49152
	s_waitcnt lgkmcnt(3)
	v_pk_mul_f32 v[30:31], v[30:31], v[50:51]
	s_waitcnt lgkmcnt(2)
	v_pk_mul_f32 v[26:27], v[26:27], v[54:55]
	s_waitcnt lgkmcnt(1)
	v_pk_mul_f32 v[22:23], v[22:23], v[58:59]
	v_pk_mul_f32 v[32:33], v[32:33], v[52:53]
	v_pk_mul_f32 v[28:29], v[28:29], v[56:57]
	v_pk_mul_f32 v[24:25], v[24:25], v[60:61]
	s_waitcnt lgkmcnt(0)
	v_pk_mul_f32 v[20:21], v[20:21], v[68:69]
	v_pk_mul_f32 v[18:19], v[18:19], v[66:67]
	v_pk_mul_f32 v[14:15], v[14:15], v[50:51]
	v_pk_mul_f32 v[10:11], v[10:11], v[54:55]
	v_pk_mul_f32 v[6:7], v[6:7], v[58:59]
	v_pk_mul_f32 v[16:17], v[16:17], v[52:53]
	v_pk_mul_f32 v[12:13], v[12:13], v[56:57]
	v_pk_mul_f32 v[8:9], v[8:9], v[60:61]
	v_pk_mul_f32 v[4:5], v[4:5], v[68:69]
	v_pk_mul_f32 v[2:3], v[2:3], v[66:67]

; #define WAIT_BAR(N) asm volatile("s_waitcnt vmcnt(" #N ") lgkmcnt(0)\n\ts_barrier" ::: "memory")
; #define RESC() do { if (resc) { asm volatile("s_waitcnt lgkmcnt(0)" ::: "memory"); \
;       _Pragma("unroll") for (int d_ = 0; d_ < 2; ++d_) _Pragma("unroll") for (int r = 0; r < 16; ++r) o[d_][r] *= wsf[crow(r, hi)]; } } while (0)
; #define ROT() do { sl_prev = sl_cur; sl_cur = sl_next; sl_next = (sl_next == (NSLOT - 1) * SLOTB) ? 0 : sl_next + SLOTB; } while (0)
; template <int THRL> __device__ __forceinline__ void attn_unit(int b, int h, int qb, const f16_t* Q, const f16_t* __restrict__ K, const f16_t* __restrict__ V, f16_t* O, const float* __restrict__ kms, char* shm) {
;     ...
;     int t = 1;
;     for (; t + 5 < NT; t += 2) {
;         STEP(pB0, pB1, pA0, pA1, t, true, true, true);     WAIT_BAR(2); RESC(); ROT();
;         STEP(pA0, pA1, pB0, pB1, t + 1, true, true, true); WAIT_BAR(2); RESC(); ROT();
.LBB0_548:
	s_waitcnt lgkmcnt(0)
	v_mfma_f32_32x32x16_f16 v[18:33], v[142:145], v[150:153], v[18:33]
	v_exp_f32_e32 v66, v66
	v_exp_f32_e32 v67, v67
	v_exp_f32_e32 v68, v68
	v_exp_f32_e32 v69, v69
	v_mfma_f32_32x32x16_f16 v[18:33], v[134:137], v[98:101], v[18:33]
	v_exp_f32_e32 v70, v70
	v_exp_f32_e32 v71, v71
	v_exp_f32_e32 v72, v72
	v_exp_f32_e32 v73, v73
	v_add_u32_e32 v94, s11, v211
	ds_read_b128 v[174:177], v94
	ds_read_b128 v[170:173], v94 offset:512
	v_mfma_f32_32x32x16_f16 v[18:33], v[126:129], v[106:109], v[18:33]
	v_exp_f32_e32 v74, v74
	v_exp_f32_e32 v75, v75
	v_exp_f32_e32 v76, v76
	v_exp_f32_e32 v77, v77
	ds_read_b128 v[166:169], v94 offset:2048
	ds_read_b128 v[162:165], v94 offset:2560
	v_mfma_f32_32x32x16_f16 v[18:33], v[122:125], v[86:89], v[18:33]
	v_exp_f32_e32 v78, v78
	v_exp_f32_e32 v79, v79
	v_exp_f32_e32 v80, v80
	v_exp_f32_e32 v81, v81
	ds_read_b128 v[158:161], v94 offset:4096
	v_mfma_f32_32x32x16_f16 v[2:17], v[142:145], v[154:157], v[2:17]
	v_exp_f32_e32 v50, v50
	v_exp_f32_e32 v51, v51
	v_exp_f32_e32 v52, v52
	v_exp_f32_e32 v53, v53
	ds_read_b128 v[150:153], v94 offset:6144
	ds_read_b128 v[146:149], v94 offset:6656
	ds_read_b128 v[154:157], v94 offset:4608
	v_mfma_f32_32x32x16_f16 v[2:17], v[134:137], v[102:105], v[2:17]
	v_exp_f32_e32 v54, v54
	v_exp_f32_e32 v55, v55
	v_exp_f32_e32 v56, v56
	v_exp_f32_e32 v57, v57
	v_mfma_f32_32x32x16_f16 v[2:17], v[126:129], v[82:85], v[2:17]
	v_exp_f32_e32 v58, v58
	v_exp_f32_e32 v59, v59
	v_exp_f32_e32 v60, v60
	v_exp_f32_e32 v61, v61
	v_mfma_f32_32x32x16_f16 v[2:17], v[122:125], v[90:93], v[2:17]
	v_exp_f32_e32 v62, v62
	v_exp_f32_e32 v63, v63
	v_exp_f32_e32 v64, v64
	v_exp_f32_e32 v65, v65
	s_waitcnt vmcnt(2) lgkmcnt(0)
	s_barrier
	s_andn2_b64 vcc, exec, s[8:9]
	s_cbranch_vccnz .LBB0_550
	s_waitcnt lgkmcnt(0)
	ds_read_b128 v[82:85], v192 offset:49248
	ds_read_b128 v[86:89], v192 offset:49216
	ds_read_b128 v[90:93], v192 offset:49184
	ds_read_b128 v[94:97], v192 offset:49152
	s_waitcnt lgkmcnt(3)
	v_pk_mul_f32 v[30:31], v[30:31], v[82:83]
	s_waitcnt lgkmcnt(2)
	v_pk_mul_f32 v[26:27], v[26:27], v[86:87]
	s_waitcnt lgkmcnt(1)
	v_pk_mul_f32 v[22:23], v[22:23], v[90:91]
	v_pk_mul_f32 v[32:33], v[32:33], v[84:85]
	v_pk_mul_f32 v[28:29], v[28:29], v[88:89]
	v_pk_mul_f32 v[24:25], v[24:25], v[92:93]
	s_waitcnt lgkmcnt(0)
	v_pk_mul_f32 v[20:21], v[20:21], v[96:97]
	v_pk_mul_f32 v[18:19], v[18:19], v[94:95]
	v_pk_mul_f32 v[14:15], v[14:15], v[82:83]
	v_pk_mul_f32 v[10:11], v[10:11], v[86:87]
	v_pk_mul_f32 v[6:7], v[6:7], v[90:91]
	v_pk_mul_f32 v[16:17], v[16:17], v[84:85]
	v_pk_mul_f32 v[12:13], v[12:13], v[88:89]
	v_pk_mul_f32 v[8:9], v[8:9], v[92:93]
	v_pk_mul_f32 v[4:5], v[4:5], v[96:97]
	v_pk_mul_f32 v[2:3], v[2:3], v[94:95]
